# v51 + 32 of the P3 epilogue 64-bit address adds done with one v_lshl_add_u64 and SGPR constants instead of add_co / s_nop / addc_co
# baseline (speedup 1.0000x reference)
; #define LAS __attribute__((address_space(3)))
; __device__ __forceinline__ unsigned xb_add(unsigned* p, unsigned v) { return __hip_atomic_fetch_add(p, v, __ATOMIC_RELAXED, __HIP_MEMORY_SCOPE_AGENT); }
; __device__ __forceinline__ unsigned xb_xcc_id() { return (unsigned)__builtin_amdgcn_s_getreg((3 << 11) | 20) & 0xFu; }
; __global__ void __launch_bounds__(512, 2) fwd_megakernel(Args args) {
;     extern __shared__ __attribute__((aligned(16))) unsigned char lds_raw[];
;     LAS unsigned char* lds = (LAS unsigned char*)lds_raw;
;     cg::grid_group grid = cg::this_grid();
;     const int wave = __builtin_amdgcn_readfirstlane(threadIdx.x >> 6);
;     const int G = gridDim.x, bx = blockIdx.x;
;     XcdBarrier xbar; xbar.bar = (unsigned*)(args.ws + 32768); xbar.x = xb_xcc_id(); xbar.st = (volatile LAS unsigned*)(lds + 138240);
;     if (threadIdx.x == 0) { xbar.st[0] = 0u; xbar.st[1] = 0u; (void)xb_add(&xbar.bar[XB_XCNT(xbar.x)], 1u); }
_Z14fwd_megakernel4Args:
	s_mov_b32 s98, 0x1000
	s_mov_b32 s99, 0
	s_mov_b32 s100, 0x2000
	s_mov_b32 s101, 0
	s_load_dwordx8 s[52:59], s[0:1], 0x80
	s_add_u32 s10, s0, 0xa0
	s_addc_u32 s11, s1, 0
	s_load_dword s28, s[0:1], 0xa0
	v_and_b32_e32 v86, 0x3ff, v0
	s_waitcnt lgkmcnt(0)
	s_add_u32 s4, s58, 0x8000
	s_addc_u32 s5, s59, 0
	v_writelane_b32 v249, s4, 0
	s_getreg_b32 s3, hwreg(HW_REG_XCC_ID, 0, 4)
	v_readfirstlane_b32 s60, v86
	v_writelane_b32 v249, s5, 1
	s_and_b32 s3, s3, 15
	v_cmp_eq_u32_e32 vcc, 0, v86
	v_writelane_b32 v249, s3, 2
	s_and_saveexec_b64 s[4:5], vcc
	s_cbranch_execz .LBB0_3
	s_add_i32 s3, 0, 0x21c00
	v_mov_b32_e32 v1, 0
	v_mov_b32_e32 v2, s3
	s_add_i32 s3, 0, 0x21c04
	s_mov_b64 s[6:7], exec
	ds_write_b32 v2, v1
	v_mov_b32_e32 v2, s3
	ds_write_b32 v2, v1
	v_mbcnt_lo_u32_b32 v1, s6, 0
	v_mbcnt_hi_u32_b32 v1, s7, v1
	v_cmp_eq_u32_e32 vcc, 0, v1
	s_and_b64 s[8:9], exec, vcc
	s_mov_b64 exec, s[8:9]
	s_cbranch_execz .LBB0_3
	v_readlane_b32 s3, v249, 2
	s_bcnt1_i32_b64 s6, s[6:7]
	s_lshl_b32 s3, s3, 8
	v_mov_b32_e32 v2, s6
	v_readlane_b32 s6, v249, 0
	v_mov_b32_e32 v1, s3
	v_readlane_b32 s7, v249, 1
	s_nop 4
	global_atomic_add v1, v2, s[6:7] offset:1024

;     __device__ __forceinline__ void operator()(const f32x4 (&acc)[2][2][4][2], const Unit& u, int wr, int wc, int fr, int fq) const {
;     ...
;         } else {
;             const int row0 = u.pm * BM + wr * 64 + fr, col0 = u.pn * BM + wc * 32 + 8 * fq;
; #pragma unroll
;             for (int ai = 0; ai < 2; ++ai) {
;                 u32x2 g[16], t[16];
; #pragma unroll
;                 for (int k = 0; k < 16; ++k) { g[k] = tg[(ai * 16 + k) * 64]; if (mode != 1) t[k] = tm[(ai * 16 + k) * 64]; }
.LBB0_553:
	v_lshl_add_u64 v[138:139], v[134:135], 0, s[98:99]
	global_load_dwordx2 v[186:187], v[138:139], off
	s_and_b64 vcc, exec, s[8:9]
	s_cbranch_vccnz .LBB0_555
	v_lshl_add_u64 v[138:139], v[136:137], 0, s[98:99]
	global_load_dwordx2 v[154:155], v[138:139], off
.LBB0_555:
	v_lshl_add_u64 v[138:139], v[134:135], 0, s[98:99]
	global_load_dwordx2 v[188:189], v[138:139], off offset:512
	s_and_b64 vcc, exec, s[8:9]
	s_cbranch_vccnz .LBB0_557
	v_lshl_add_u64 v[138:139], v[136:137], 0, s[98:99]
	global_load_dwordx2 v[156:157], v[138:139], off offset:512
.LBB0_557:
	v_lshl_add_u64 v[138:139], v[134:135], 0, s[98:99]
	global_load_dwordx2 v[182:183], v[138:139], off offset:1024
	s_and_b64 vcc, exec, s[8:9]
	s_cbranch_vccnz .LBB0_559
	v_lshl_add_u64 v[138:139], v[136:137], 0, s[98:99]
	global_load_dwordx2 v[150:151], v[138:139], off offset:1024
.LBB0_559:
	v_lshl_add_u64 v[138:139], v[134:135], 0, s[98:99]
	global_load_dwordx2 v[184:185], v[138:139], off offset:1536
	s_and_b64 vcc, exec, s[8:9]
	s_cbranch_vccnz .LBB0_561
	v_lshl_add_u64 v[138:139], v[136:137], 0, s[98:99]
	global_load_dwordx2 v[152:153], v[138:139], off offset:1536
.LBB0_561:
	v_lshl_add_u64 v[138:139], v[134:135], 0, s[98:99]
	global_load_dwordx2 v[178:179], v[138:139], off offset:2048
	s_and_b64 vcc, exec, s[8:9]
	s_cbranch_vccnz .LBB0_563
	v_lshl_add_u64 v[138:139], v[136:137], 0, s[98:99]
	global_load_dwordx2 v[146:147], v[138:139], off offset:2048
.LBB0_563:
	v_lshl_add_u64 v[138:139], v[134:135], 0, s[98:99]
	global_load_dwordx2 v[180:181], v[138:139], off offset:2560
	s_and_b64 vcc, exec, s[8:9]
	s_cbranch_vccnz .LBB0_565
	v_lshl_add_u64 v[138:139], v[136:137], 0, s[98:99]
	global_load_dwordx2 v[148:149], v[138:139], off offset:2560
.LBB0_565:
	v_lshl_add_u64 v[138:139], v[134:135], 0, s[98:99]
	global_load_dwordx2 v[174:175], v[138:139], off offset:3072
	s_and_b64 vcc, exec, s[8:9]
	s_cbranch_vccnz .LBB0_567
	v_lshl_add_u64 v[138:139], v[136:137], 0, s[98:99]
	global_load_dwordx2 v[138:139], v[138:139], off offset:3072
.LBB0_567:
	v_lshl_add_u64 v[140:141], v[134:135], 0, s[98:99]
	global_load_dwordx2 v[176:177], v[140:141], off offset:3584
	s_and_b64 vcc, exec, s[8:9]
	s_cbranch_vccnz .LBB0_569
	v_lshl_add_u64 v[140:141], v[136:137], 0, s[98:99]
	global_load_dwordx2 v[140:141], v[140:141], off offset:3584

;     __device__ __forceinline__ void operator()(const f32x4 (&acc)[2][2][4][2], const Unit& u, int wr, int wc, int fr, int fq) const {
;     ...
;         } else {
;             const int row0 = u.pm * BM + wr * 64 + fr, col0 = u.pn * BM + wc * 32 + 8 * fq;
; #pragma unroll
;             for (int ai = 0; ai < 2; ++ai) {
;                 u32x2 g[16], t[16];
; #pragma unroll
;                 for (int k = 0; k < 16; ++k) { g[k] = tg[(ai * 16 + k) * 64]; if (mode != 1) t[k] = tm[(ai * 16 + k) * 64]; }
.LBB0_605:
	v_lshl_add_u64 v[174:175], v[134:135], 0, s[100:101]
	global_load_dwordx2 v[202:203], v[174:175], off
	s_and_b64 vcc, exec, s[8:9]
	s_cbranch_vccnz .LBB0_607
	v_lshl_add_u64 v[172:173], v[136:137], 0, s[100:101]
	global_load_dwordx2 v[172:173], v[172:173], off
.LBB0_607:
	v_lshl_add_u64 v[174:175], v[134:135], 0, s[100:101]
	global_load_dwordx2 v[204:205], v[174:175], off offset:512
	s_and_b64 vcc, exec, s[8:9]
	s_cbranch_vccnz .LBB0_609
	v_lshl_add_u64 v[170:171], v[136:137], 0, s[100:101]
	global_load_dwordx2 v[170:171], v[170:171], off offset:512
.LBB0_609:
	v_lshl_add_u64 v[174:175], v[134:135], 0, s[100:101]
	global_load_dwordx2 v[198:199], v[174:175], off offset:1024
	s_and_b64 vcc, exec, s[8:9]
	s_cbranch_vccnz .LBB0_611
	v_lshl_add_u64 v[168:169], v[136:137], 0, s[100:101]
	global_load_dwordx2 v[168:169], v[168:169], off offset:1024
.LBB0_611:
	v_lshl_add_u64 v[174:175], v[134:135], 0, s[100:101]
	global_load_dwordx2 v[200:201], v[174:175], off offset:1536
	s_and_b64 vcc, exec, s[8:9]
	s_cbranch_vccnz .LBB0_613
	v_lshl_add_u64 v[166:167], v[136:137], 0, s[100:101]
	global_load_dwordx2 v[166:167], v[166:167], off offset:1536
.LBB0_613:
	v_lshl_add_u64 v[174:175], v[134:135], 0, s[100:101]
	global_load_dwordx2 v[194:195], v[174:175], off offset:2048
	s_and_b64 vcc, exec, s[8:9]
	s_cbranch_vccnz .LBB0_615
	v_lshl_add_u64 v[164:165], v[136:137], 0, s[100:101]
	global_load_dwordx2 v[164:165], v[164:165], off offset:2048
.LBB0_615:
	v_lshl_add_u64 v[174:175], v[134:135], 0, s[100:101]
	global_load_dwordx2 v[196:197], v[174:175], off offset:2560
	s_and_b64 vcc, exec, s[8:9]
	s_cbranch_vccnz .LBB0_617
	v_lshl_add_u64 v[162:163], v[136:137], 0, s[100:101]
	global_load_dwordx2 v[162:163], v[162:163], off offset:2560
.LBB0_617:
	v_lshl_add_u64 v[174:175], v[134:135], 0, s[100:101]
	global_load_dwordx2 v[190:191], v[174:175], off offset:3072
	s_and_b64 vcc, exec, s[8:9]
	s_cbranch_vccnz .LBB0_619
	v_lshl_add_u64 v[160:161], v[136:137], 0, s[100:101]
	global_load_dwordx2 v[160:161], v[160:161], off offset:3072
.LBB0_619:
	v_lshl_add_u64 v[174:175], v[134:135], 0, s[100:101]
	global_load_dwordx2 v[192:193], v[174:175], off offset:3584
	s_and_b64 vcc, exec, s[8:9]
	s_cbranch_vccnz .LBB0_621
	v_lshl_add_u64 v[158:159], v[136:137], 0, s[100:101]
	global_load_dwordx2 v[158:159], v[158:159], off offset:3584
